# P5: h1 (bf16) and E stores nt (no dirty lines left for the quad release fence)
# speedup vs baseline: 1.0066x; 1.0066x over previous
; __device__ __forceinline__ unsigned cvt_pk_bf16_v(float lo, float hi) { const f32x2c v = {lo, hi}; const bf16x2c b = __builtin_convertvector(v, bf16x2c); return __builtin_bit_cast(unsigned, b); }
;     __device__ __forceinline__ void operator()(const f32x4 (&acc)[2][2][4][2], const Unit& u_, int wr, int wc, int fr, int fq) const {
;     ...
;                     for (int t = 0; t < 2; ++t) xr[m][bj][t] = *(const f32x4*)(xp + (size_t)(rowb + ai * HALF + m * 16 + 8 * t) * 1024 + colb + bj * HALF);
;             asm volatile("" ::: "memory");
; #pragma unroll
;             for (int m = 0; m < 4; ++m)
; #pragma unroll
;                 for (int bj = 0; bj < 2; ++bj) { f32x4 o[2]; xchg_f32(xl, fr, fq, l, acc[ai][bj][m][0], acc[ai][bj][m][1], o[0], o[1]);
; #pragma unroll
;                     for (int t = 0; t < 2; ++t) { const f32x4 v = o[t] + xr[m][bj][t]; u32x2 w; w.x = cvt_pk_bf16_v(v[0], v[1]); w.y = cvt_pk_bf16_v(v[2], v[3]);
;                         *(u32x2*)(h1b + (size_t)(rowb + ai * HALF + m * 16 + 8 * t) * 1024 + colb + bj * HALF) = w; } }
;             asm volatile("" ::: "memory");
.LBB0_836:
	s_mov_b64 s[56:57], -1
	v_lshl_add_u32 v206, s8, 8, v233
	v_lshl_or_b32 v222, s9, 8, v234
	v_ashrrev_i32_e32 v223, 31, v222
	v_ashrrev_i32_e32 v207, 31, v206
	v_lshl_add_u64 v[204:205], v[222:223], 2, s[68:69]
	v_lshlrev_b64 v[130:131], 12, v[206:207]
	v_or_b32_e32 v220, 8, v206
	v_lshl_add_u64 v[130:131], v[204:205], 0, v[130:131]
	v_ashrrev_i32_e32 v221, 31, v220
	global_load_dwordx4 v[238:241], v[130:131], off
	v_lshlrev_b64 v[132:133], 12, v[220:221]
	v_lshl_add_u64 v[132:133], v[204:205], 0, v[132:133]
	global_load_dwordx4 v[242:245], v[132:133], off
	global_load_dwordx4 v[178:181], v[130:131], off offset:512
	global_load_dwordx4 v[182:185], v[132:133], off offset:512
	v_or_b32_e32 v218, 16, v206
	v_ashrrev_i32_e32 v219, 31, v218
	v_lshlrev_b64 v[130:131], 12, v[218:219]
	v_lshl_add_u64 v[130:131], v[204:205], 0, v[130:131]
	global_load_dwordx4 v[174:177], v[130:131], off
	v_or_b32_e32 v216, 24, v206
	v_ashrrev_i32_e32 v217, 31, v216
	v_lshlrev_b64 v[132:133], 12, v[216:217]
	v_lshl_add_u64 v[132:133], v[204:205], 0, v[132:133]
	global_load_dwordx4 v[170:173], v[132:133], off
	global_load_dwordx4 v[166:169], v[130:131], off offset:512
	global_load_dwordx4 v[162:165], v[132:133], off offset:512
	v_or_b32_e32 v212, 32, v206
	v_ashrrev_i32_e32 v213, 31, v212
	v_lshlrev_b64 v[130:131], 12, v[212:213]
	v_lshl_add_u64 v[130:131], v[204:205], 0, v[130:131]
	global_load_dwordx4 v[154:157], v[130:131], off
	v_or_b32_e32 v214, 40, v206
	v_ashrrev_i32_e32 v215, 31, v214
	v_lshlrev_b64 v[132:133], 12, v[214:215]
	v_lshl_add_u64 v[132:133], v[204:205], 0, v[132:133]
	global_load_dwordx4 v[158:161], v[132:133], off
	global_load_dwordx4 v[146:149], v[130:131], off offset:512
	global_load_dwordx4 v[142:145], v[132:133], off offset:512
	v_or_b32_e32 v208, 48, v206
	v_ashrrev_i32_e32 v209, 31, v208
	v_lshlrev_b64 v[130:131], 12, v[208:209]
	v_lshl_add_u64 v[130:131], v[204:205], 0, v[130:131]
	global_load_dwordx4 v[138:141], v[130:131], off
	v_or_b32_e32 v210, 56, v206
	v_ashrrev_i32_e32 v211, 31, v210
	v_lshlrev_b64 v[132:133], 12, v[210:211]
	v_lshl_add_u64 v[132:133], v[204:205], 0, v[132:133]
	global_load_dwordx4 v[150:153], v[132:133], off
	global_load_dwordx4 v[134:137], v[130:131], off offset:512
	s_nop 0
	global_load_dwordx4 v[130:133], v[132:133], off offset:512
	ds_write_b128 v236, v[126:129]
	ds_write_b128 v236, v[122:125] offset:16
	ds_read_b128 v[122:125], v237
	ds_read_b128 v[126:129], v237 offset:1152
	s_cmp_eq_u32 s74, s72
	s_waitcnt vmcnt(0) lgkmcnt(0)
	v_pk_add_f32 v[122:123], v[238:239], v[122:123]
	v_pk_add_f32 v[128:129], v[244:245], v[128:129]
	v_pk_add_f32 v[126:127], v[242:243], v[126:127]
	v_pk_add_f32 v[124:125], v[240:241], v[124:125]
	v_cvt_pk_bf16_f32 v238, v122, v123
	v_lshlrev_b64 v[122:123], 11, v[206:207]
	v_cvt_pk_bf16_f32 v126, v126, v127
	v_cvt_pk_bf16_f32 v127, v128, v129
	v_lshlrev_b64 v[128:129], 11, v[220:221]
	v_cvt_pk_bf16_f32 v239, v124, v125
	v_lshl_add_u64 v[124:125], s[14:15], 0, v[122:123]
	v_lshlrev_b64 v[122:123], 1, v[222:223]
	v_lshl_add_u64 v[128:129], s[14:15], 0, v[128:129]
	v_lshl_add_u64 v[124:125], v[124:125], 0, v[122:123]
	v_lshl_add_u64 v[128:129], v[128:129], 0, v[122:123]
	global_store_dwordx2 v[124:125], v[238:239], off nt
	global_store_dwordx2 v[128:129], v[126:127], off nt
	ds_write_b128 v236, v[118:121]
	ds_write_b128 v236, v[114:117] offset:16
	ds_read_b128 v[114:117], v237
	ds_read_b128 v[118:121], v237 offset:1152
	s_waitcnt lgkmcnt(1)
	v_pk_add_f32 v[116:117], v[180:181], v[116:117]
	v_pk_add_f32 v[114:115], v[178:179], v[114:115]
	s_nop 0
	v_cvt_pk_bf16_f32 v114, v114, v115
	v_cvt_pk_bf16_f32 v115, v116, v117
	global_store_dwordx2 v[124:125], v[114:115], off offset:256 nt
	s_waitcnt lgkmcnt(0)
	v_pk_add_f32 v[114:115], v[184:185], v[120:121]
	v_pk_add_f32 v[116:117], v[182:183], v[118:119]
	s_nop 0
	v_cvt_pk_bf16_f32 v116, v116, v117
	v_cvt_pk_bf16_f32 v117, v114, v115
	global_store_dwordx2 v[128:129], v[116:117], off offset:256 nt
	ds_write_b128 v236, v[110:113]
	ds_write_b128 v236, v[106:109] offset:16
	ds_read_b128 v[106:109], v237
	ds_read_b128 v[110:113], v237 offset:1152
	s_waitcnt lgkmcnt(1)
	v_pk_add_f32 v[108:109], v[176:177], v[108:109]
	v_pk_add_f32 v[106:107], v[174:175], v[106:107]
	s_waitcnt lgkmcnt(0)
	v_pk_add_f32 v[110:111], v[170:171], v[110:111]
	v_cvt_pk_bf16_f32 v106, v106, v107
	v_cvt_pk_bf16_f32 v107, v108, v109
	v_lshlrev_b64 v[108:109], 11, v[218:219]
	v_lshl_add_u64 v[108:109], s[14:15], 0, v[108:109]
	v_lshl_add_u64 v[108:109], v[108:109], 0, v[122:123]
	global_store_dwordx2 v[108:109], v[106:107], off nt
	v_pk_add_f32 v[106:107], v[172:173], v[112:113]
	v_cvt_pk_bf16_f32 v110, v110, v111
	v_cvt_pk_bf16_f32 v111, v106, v107
	v_lshlrev_b64 v[106:107], 11, v[216:217]
	v_lshl_add_u64 v[106:107], s[14:15], 0, v[106:107]
	v_lshl_add_u64 v[106:107], v[106:107], 0, v[122:123]
	global_store_dwordx2 v[106:107], v[110:111], off nt
	ds_write_b128 v236, v[102:105]
	ds_write_b128 v236, v[98:101] offset:16
	ds_read_b128 v[98:101], v237
	ds_read_b128 v[102:105], v237 offset:1152
	s_waitcnt lgkmcnt(1)
	v_pk_add_f32 v[100:101], v[168:169], v[100:101]
	v_pk_add_f32 v[98:99], v[166:167], v[98:99]
	s_nop 0
	v_cvt_pk_bf16_f32 v98, v98, v99
	v_cvt_pk_bf16_f32 v99, v100, v101
	global_store_dwordx2 v[108:109], v[98:99], off offset:256 nt
	s_waitcnt lgkmcnt(0)
	v_pk_add_f32 v[98:99], v[164:165], v[104:105]
	v_pk_add_f32 v[100:101], v[162:163], v[102:103]
	v_add_u32_e32 v104, 0xa0, v206
	v_cvt_pk_bf16_f32 v100, v100, v101
	v_cvt_pk_bf16_f32 v101, v98, v99
	global_store_dwordx2 v[106:107], v[100:101], off offset:256 nt
	ds_write_b128 v236, v[94:97]
	ds_write_b128 v236, v[90:93] offset:16
	ds_read_b128 v[90:93], v237
	ds_read_b128 v[94:97], v237 offset:1152
	v_ashrrev_i32_e32 v105, 31, v104
	v_add_u32_e32 v102, 0xa8, v206
	v_ashrrev_i32_e32 v103, 31, v102
	s_waitcnt lgkmcnt(1)
; __device__ __forceinline__ unsigned cvt_pk_bf16_v(float lo, float hi) { const f32x2c v = {lo, hi}; const bf16x2c b = __builtin_convertvector(v, bf16x2c); return __builtin_bit_cast(unsigned, b); }
;     __device__ __forceinline__ void operator()(const f32x4 (&acc)[2][2][4][2], const Unit& u_, int wr, int wc, int fr, int fq) const {
;     ...
;                     for (int t = 0; t < 2; ++t) xr[m][bj][t] = *(const f32x4*)(xp + (size_t)(rowb + ai * HALF + m * 16 + 8 * t) * 1024 + colb + bj * HALF);
;             asm volatile("" ::: "memory");
; #pragma unroll
;             for (int m = 0; m < 4; ++m)
; #pragma unroll
;                 for (int bj = 0; bj < 2; ++bj) { f32x4 o[2]; xchg_f32(xl, fr, fq, l, acc[ai][bj][m][0], acc[ai][bj][m][1], o[0], o[1]);
; #pragma unroll
;                     for (int t = 0; t < 2; ++t) { const f32x4 v = o[t] + xr[m][bj][t]; u32x2 w; w.x = cvt_pk_bf16_v(v[0], v[1]); w.y = cvt_pk_bf16_v(v[2], v[3]);
;                         *(u32x2*)(h1b + (size_t)(rowb + ai * HALF + m * 16 + 8 * t) * 1024 + colb + bj * HALF) = w; } }
;             asm volatile("" ::: "memory");
	v_pk_add_f32 v[92:93], v[156:157], v[92:93]
	v_pk_add_f32 v[90:91], v[154:155], v[90:91]
	s_waitcnt lgkmcnt(0)
	v_pk_add_f32 v[94:95], v[158:159], v[94:95]
	v_cvt_pk_bf16_f32 v90, v90, v91
	v_cvt_pk_bf16_f32 v91, v92, v93
	v_lshlrev_b64 v[92:93], 11, v[212:213]
	v_lshl_add_u64 v[92:93], s[14:15], 0, v[92:93]
	v_lshl_add_u64 v[92:93], v[92:93], 0, v[122:123]
	global_store_dwordx2 v[92:93], v[90:91], off nt
	v_pk_add_f32 v[90:91], v[160:161], v[96:97]
	v_cvt_pk_bf16_f32 v94, v94, v95
	v_cvt_pk_bf16_f32 v95, v90, v91
	v_lshlrev_b64 v[90:91], 11, v[214:215]
	v_lshl_add_u64 v[90:91], s[14:15], 0, v[90:91]
	v_lshl_add_u64 v[90:91], v[90:91], 0, v[122:123]
	global_store_dwordx2 v[90:91], v[94:95], off nt
	ds_write_b128 v236, v[86:89]
	ds_write_b128 v236, v[82:85] offset:16
	ds_read_b128 v[82:85], v237
	ds_read_b128 v[86:89], v237 offset:1152
	v_add_u32_e32 v100, 0xb0, v206
	v_ashrrev_i32_e32 v101, 31, v100
	v_add_u32_e32 v98, 0xb8, v206
	s_waitcnt lgkmcnt(1)
	v_pk_add_f32 v[84:85], v[148:149], v[84:85]
	v_pk_add_f32 v[82:83], v[146:147], v[82:83]
	v_add_u32_e32 v146, 0x98, v206
	v_cvt_pk_bf16_f32 v82, v82, v83
	v_cvt_pk_bf16_f32 v83, v84, v85
	global_store_dwordx2 v[92:93], v[82:83], off offset:256 nt
	s_waitcnt lgkmcnt(0)
	v_pk_add_f32 v[82:83], v[144:145], v[88:89]
	v_pk_add_f32 v[84:85], v[142:143], v[86:87]
	v_add_u32_e32 v142, 0x88, v206
	v_cvt_pk_bf16_f32 v84, v84, v85
	v_cvt_pk_bf16_f32 v85, v82, v83
	global_store_dwordx2 v[90:91], v[84:85], off offset:256 nt
	ds_write_b128 v236, v[78:81]
	ds_write_b128 v236, v[74:77] offset:16
	ds_read_b128 v[74:77], v237
	ds_read_b128 v[78:81], v237 offset:1152
	v_ashrrev_i32_e32 v143, 31, v142
	v_add_u32_e32 v144, 0x90, v206
	v_ashrrev_i32_e32 v145, 31, v144
	s_waitcnt lgkmcnt(1)
	v_pk_add_f32 v[76:77], v[140:141], v[76:77]
	v_pk_add_f32 v[74:75], v[138:139], v[74:75]
	s_waitcnt lgkmcnt(0)
	v_pk_add_f32 v[78:79], v[150:151], v[78:79]
	v_cvt_pk_bf16_f32 v74, v74, v75
	v_cvt_pk_bf16_f32 v75, v76, v77
	v_lshlrev_b64 v[76:77], 11, v[208:209]
	v_lshl_add_u64 v[76:77], s[14:15], 0, v[76:77]
	v_lshl_add_u64 v[76:77], v[76:77], 0, v[122:123]
	global_store_dwordx2 v[76:77], v[74:75], off nt
	v_pk_add_f32 v[74:75], v[152:153], v[80:81]
	v_cvt_pk_bf16_f32 v78, v78, v79
	v_cvt_pk_bf16_f32 v79, v74, v75
	v_lshlrev_b64 v[74:75], 11, v[210:211]
	v_lshl_add_u64 v[74:75], s[14:15], 0, v[74:75]
	v_lshl_add_u64 v[74:75], v[74:75], 0, v[122:123]
	global_store_dwordx2 v[74:75], v[78:79], off nt
	ds_write_b128 v236, v[70:73]
	ds_write_b128 v236, v[66:69] offset:16
	ds_read_b128 v[66:69], v237
	ds_read_b128 v[70:73], v237 offset:1152
	v_add_u32_e32 v140, 0x80, v206
	v_ashrrev_i32_e32 v141, 31, v140
	v_ashrrev_i32_e32 v147, 31, v146
	s_waitcnt lgkmcnt(1)
	v_pk_add_f32 v[68:69], v[136:137], v[68:69]
	v_pk_add_f32 v[66:67], v[134:135], v[66:67]
	v_ashrrev_i32_e32 v99, 31, v98
	v_cvt_pk_bf16_f32 v66, v66, v67
	v_cvt_pk_bf16_f32 v67, v68, v69
	global_store_dwordx2 v[76:77], v[66:67], off offset:256 nt
	s_waitcnt lgkmcnt(0)
	v_pk_add_f32 v[66:67], v[132:133], v[72:73]
	v_pk_add_f32 v[68:69], v[130:131], v[70:71]
	s_nop 0
	v_cvt_pk_bf16_f32 v68, v68, v69
	v_cvt_pk_bf16_f32 v69, v66, v67
	global_store_dwordx2 v[74:75], v[68:69], off offset:256 nt
	v_lshlrev_b64 v[66:67], 12, v[140:141]
	v_lshl_add_u64 v[66:67], v[204:205], 0, v[66:67]
	global_load_dwordx4 v[106:109], v[66:67], off
	v_lshlrev_b64 v[68:69], 12, v[142:143]
	v_lshl_add_u64 v[68:69], v[204:205], 0, v[68:69]
	global_load_dwordx4 v[110:113], v[68:69], off
	global_load_dwordx4 v[114:117], v[66:67], off offset:512
	global_load_dwordx4 v[118:121], v[68:69], off offset:512
	v_lshlrev_b64 v[66:67], 12, v[144:145]
	v_lshl_add_u64 v[66:67], v[204:205], 0, v[66:67]
	global_load_dwordx4 v[124:127], v[66:67], off
	v_lshlrev_b64 v[68:69], 12, v[146:147]
	v_lshl_add_u64 v[68:69], v[204:205], 0, v[68:69]
	global_load_dwordx4 v[128:131], v[68:69], off
	global_load_dwordx4 v[132:135], v[66:67], off offset:512
	global_load_dwordx4 v[136:139], v[68:69], off offset:512
	v_lshlrev_b64 v[66:67], 12, v[104:105]
	v_lshl_add_u64 v[66:67], v[204:205], 0, v[66:67]
	global_load_dwordx4 v[94:97], v[66:67], off
	v_lshlrev_b64 v[68:69], 12, v[102:103]
	v_lshl_add_u64 v[68:69], v[204:205], 0, v[68:69]
	global_load_dwordx4 v[90:93], v[68:69], off
	global_load_dwordx4 v[86:89], v[66:67], off offset:512
	global_load_dwordx4 v[82:85], v[68:69], off offset:512
	v_lshlrev_b64 v[66:67], 12, v[100:101]
	v_lshl_add_u64 v[66:67], v[204:205], 0, v[66:67]
	global_load_dwordx4 v[78:81], v[66:67], off
	v_lshlrev_b64 v[68:69], 12, v[98:99]
	v_lshl_add_u64 v[68:69], v[204:205], 0, v[68:69]
	global_load_dwordx4 v[74:77], v[68:69], off
	global_load_dwordx4 v[70:73], v[66:67], off offset:512
	s_nop 0
	global_load_dwordx4 v[66:69], v[68:69], off offset:512
	ds_write_b128 v236, v[62:65]
	ds_write_b128 v236, v[58:61] offset:16
	ds_read_b128 v[58:61], v237
	ds_read_b128 v[62:65], v237 offset:1152
	s_waitcnt vmcnt(15) lgkmcnt(1)
	v_pk_add_f32 v[60:61], v[108:109], v[60:61]
	v_pk_add_f32 v[58:59], v[106:107], v[58:59]
	s_waitcnt vmcnt(14) lgkmcnt(0)
	v_pk_add_f32 v[62:63], v[110:111], v[62:63]
	v_cvt_pk_bf16_f32 v58, v58, v59
	v_cvt_pk_bf16_f32 v59, v60, v61
	v_lshlrev_b64 v[60:61], 11, v[140:141]
	v_lshl_add_u64 v[60:61], s[14:15], 0, v[60:61]
	v_lshl_add_u64 v[60:61], v[60:61], 0, v[122:123]
	global_store_dwordx2 v[60:61], v[58:59], off nt
	v_pk_add_f32 v[58:59], v[112:113], v[64:65]
	v_cvt_pk_bf16_f32 v62, v62, v63
	v_cvt_pk_bf16_f32 v63, v58, v59
	v_lshlrev_b64 v[58:59], 11, v[142:143]
	v_lshl_add_u64 v[58:59], s[14:15], 0, v[58:59]
	v_lshl_add_u64 v[58:59], v[58:59], 0, v[122:123]
	global_store_dwordx2 v[58:59], v[62:63], off nt
	ds_write_b128 v236, v[54:57]
	ds_write_b128 v236, v[50:53] offset:16
	ds_read_b128 v[50:53], v237
	ds_read_b128 v[54:57], v237 offset:1152
	s_waitcnt vmcnt(15) lgkmcnt(1)
; __device__ __forceinline__ unsigned cvt_pk_bf16_v(float lo, float hi) { const f32x2c v = {lo, hi}; const bf16x2c b = __builtin_convertvector(v, bf16x2c); return __builtin_bit_cast(unsigned, b); }
; #define PG8_BAR __builtin_amdgcn_s_barrier()
;     __device__ __forceinline__ void operator()(const f32x4 (&acc)[2][2][4][2], const Unit& u_, int wr, int wc, int fr, int fq) const {
;     ...
;                 for (int bj = 0; bj < 2; ++bj) { f32x4 o[2]; xchg_f32(xl, fr, fq, l, acc[ai][bj][m][0], acc[ai][bj][m][1], o[0], o[1]);
; #pragma unroll
;                     for (int t = 0; t < 2; ++t) { const f32x4 v = o[t] + xr[m][bj][t]; u32x2 w; w.x = cvt_pk_bf16_v(v[0], v[1]); w.y = cvt_pk_bf16_v(v[2], v[3]);
;                         *(u32x2*)(h1b + (size_t)(rowb + ai * HALF + m * 16 + 8 * t) * 1024 + colb + bj * HALF) = w; } }
;             asm volatile("" ::: "memory");
; template <class Epi, class Sched, bool ALIGN_EPI = false, bool SP2 = false>
; __device__ __forceinline__ void gemm_phase(PG8_LAS unsigned char* lds, const Gemm g, const Sched& S, const Epi& E) {
;     ...
;         if constexpr (ALIGN_EPI) { if (wr == 0) PG8_BAR; }
;         if constexpr (!Epi::AFTER_DRAIN) { E(acc, cur, wr, wc, fr, fq); S.done(cur); }
;         if (!has_next) break;
; #pragma unroll
;         for (int a = 0; a < 2; ++a)
; #pragma unroll
;             for (int b = 0; b < 2; ++b)
; #pragma unroll
;                 for (int m = 0; m < 4; ++m)
; #pragma unroll
;                     for (int n = 0; n < 2; ++n) acc[a][b][m][n] = (f32x4){0.f, 0.f, 0.f, 0.f};
;         cur = nxt; cA = nA; cB = nB; ++ui;
;         if constexpr (ALIGN_EPI) { if (wr == 1) PG8_BAR; }
;     }
	v_pk_add_f32 v[52:53], v[116:117], v[52:53]
	v_pk_add_f32 v[50:51], v[114:115], v[50:51]
	s_nop 0
	v_cvt_pk_bf16_f32 v50, v50, v51
	v_cvt_pk_bf16_f32 v51, v52, v53
	global_store_dwordx2 v[60:61], v[50:51], off offset:256 nt
	s_waitcnt vmcnt(15) lgkmcnt(0)
	v_pk_add_f32 v[50:51], v[120:121], v[56:57]
	v_pk_add_f32 v[52:53], v[118:119], v[54:55]
	s_nop 0
	v_cvt_pk_bf16_f32 v52, v52, v53
	v_cvt_pk_bf16_f32 v53, v50, v51
	global_store_dwordx2 v[58:59], v[52:53], off offset:256 nt
	ds_write_b128 v236, v[46:49]
	ds_write_b128 v236, v[42:45] offset:16
	ds_read_b128 v[42:45], v237
	ds_read_b128 v[46:49], v237 offset:1152
	s_waitcnt vmcnt(15) lgkmcnt(1)
	v_pk_add_f32 v[44:45], v[126:127], v[44:45]
	v_pk_add_f32 v[42:43], v[124:125], v[42:43]
	s_waitcnt vmcnt(14) lgkmcnt(0)
	v_pk_add_f32 v[46:47], v[128:129], v[46:47]
	v_cvt_pk_bf16_f32 v42, v42, v43
	v_cvt_pk_bf16_f32 v43, v44, v45
	v_lshlrev_b64 v[44:45], 11, v[144:145]
	v_lshl_add_u64 v[44:45], s[14:15], 0, v[44:45]
	v_lshl_add_u64 v[44:45], v[44:45], 0, v[122:123]
	global_store_dwordx2 v[44:45], v[42:43], off nt
	v_pk_add_f32 v[42:43], v[130:131], v[48:49]
	v_cvt_pk_bf16_f32 v46, v46, v47
	v_cvt_pk_bf16_f32 v47, v42, v43
	v_lshlrev_b64 v[42:43], 11, v[146:147]
	v_lshl_add_u64 v[42:43], s[14:15], 0, v[42:43]
	v_lshl_add_u64 v[42:43], v[42:43], 0, v[122:123]
	global_store_dwordx2 v[42:43], v[46:47], off nt
	ds_write_b128 v236, v[38:41]
	ds_write_b128 v236, v[34:37] offset:16
	ds_read_b128 v[34:37], v237
	ds_read_b128 v[38:41], v237 offset:1152
	s_waitcnt vmcnt(15) lgkmcnt(1)
	v_pk_add_f32 v[36:37], v[134:135], v[36:37]
	v_pk_add_f32 v[34:35], v[132:133], v[34:35]
	s_nop 0
	v_cvt_pk_bf16_f32 v34, v34, v35
	v_cvt_pk_bf16_f32 v35, v36, v37
	global_store_dwordx2 v[44:45], v[34:35], off offset:256 nt
	s_waitcnt vmcnt(15) lgkmcnt(0)
	v_pk_add_f32 v[34:35], v[138:139], v[40:41]
	v_pk_add_f32 v[36:37], v[136:137], v[38:39]
	s_nop 0
	v_cvt_pk_bf16_f32 v36, v36, v37
	v_cvt_pk_bf16_f32 v37, v34, v35
	global_store_dwordx2 v[42:43], v[36:37], off offset:256 nt
	ds_write_b128 v236, v[30:33]
	ds_write_b128 v236, v[26:29] offset:16
	ds_read_b128 v[26:29], v237
	ds_read_b128 v[30:33], v237 offset:1152
	s_waitcnt vmcnt(15) lgkmcnt(1)
	v_pk_add_f32 v[28:29], v[96:97], v[28:29]
	v_pk_add_f32 v[26:27], v[94:95], v[26:27]
	s_waitcnt vmcnt(14) lgkmcnt(0)
	v_pk_add_f32 v[30:31], v[90:91], v[30:31]
	v_cvt_pk_bf16_f32 v26, v26, v27
	v_cvt_pk_bf16_f32 v27, v28, v29
	v_lshlrev_b64 v[28:29], 11, v[104:105]
	v_lshl_add_u64 v[28:29], s[14:15], 0, v[28:29]
	v_lshl_add_u64 v[28:29], v[28:29], 0, v[122:123]
	global_store_dwordx2 v[28:29], v[26:27], off nt
	v_pk_add_f32 v[26:27], v[92:93], v[32:33]
	v_cvt_pk_bf16_f32 v30, v30, v31
	v_cvt_pk_bf16_f32 v31, v26, v27
	v_lshlrev_b64 v[26:27], 11, v[102:103]
	v_lshl_add_u64 v[26:27], s[14:15], 0, v[26:27]
	v_lshl_add_u64 v[26:27], v[26:27], 0, v[122:123]
	global_store_dwordx2 v[26:27], v[30:31], off nt
	ds_write_b128 v236, v[22:25]
	ds_write_b128 v236, v[18:21] offset:16
	ds_read_b128 v[18:21], v237
	ds_read_b128 v[22:25], v237 offset:1152
	s_waitcnt vmcnt(15) lgkmcnt(1)
	v_pk_add_f32 v[20:21], v[88:89], v[20:21]
	v_pk_add_f32 v[18:19], v[86:87], v[18:19]
	s_nop 0
	v_cvt_pk_bf16_f32 v18, v18, v19
	v_cvt_pk_bf16_f32 v19, v20, v21
	global_store_dwordx2 v[28:29], v[18:19], off offset:256 nt
	s_waitcnt vmcnt(15) lgkmcnt(0)
	v_pk_add_f32 v[18:19], v[84:85], v[24:25]
	v_pk_add_f32 v[20:21], v[82:83], v[22:23]
	s_nop 0
	v_cvt_pk_bf16_f32 v20, v20, v21
	v_cvt_pk_bf16_f32 v21, v18, v19
	global_store_dwordx2 v[26:27], v[20:21], off offset:256 nt
	ds_write_b128 v236, v[14:17]
	ds_write_b128 v236, v[10:13] offset:16
	ds_read_b128 v[10:13], v237
	ds_read_b128 v[14:17], v237 offset:1152
	s_waitcnt vmcnt(15) lgkmcnt(1)
	v_pk_add_f32 v[12:13], v[80:81], v[12:13]
	v_pk_add_f32 v[10:11], v[78:79], v[10:11]
	s_waitcnt vmcnt(14) lgkmcnt(0)
	v_pk_add_f32 v[14:15], v[74:75], v[14:15]
	v_cvt_pk_bf16_f32 v10, v10, v11
	v_cvt_pk_bf16_f32 v11, v12, v13
	v_lshlrev_b64 v[12:13], 11, v[100:101]
	v_lshl_add_u64 v[12:13], s[14:15], 0, v[12:13]
	v_lshl_add_u64 v[12:13], v[12:13], 0, v[122:123]
	global_store_dwordx2 v[12:13], v[10:11], off nt
	v_pk_add_f32 v[10:11], v[76:77], v[16:17]
	v_cvt_pk_bf16_f32 v14, v14, v15
	v_cvt_pk_bf16_f32 v15, v10, v11
	v_lshlrev_b64 v[10:11], 11, v[98:99]
	v_lshl_add_u64 v[10:11], s[14:15], 0, v[10:11]
	v_lshl_add_u64 v[10:11], v[10:11], 0, v[122:123]
	global_store_dwordx2 v[10:11], v[14:15], off nt
	ds_write_b128 v236, v[6:9]
	ds_write_b128 v236, v[2:5] offset:16
	ds_read_b128 v[2:5], v237
	ds_read_b128 v[6:9], v237 offset:1152
	s_waitcnt vmcnt(15) lgkmcnt(1)
	v_pk_add_f32 v[4:5], v[72:73], v[4:5]
	v_pk_add_f32 v[2:3], v[70:71], v[2:3]
	s_nop 0
	v_cvt_pk_bf16_f32 v2, v2, v3
	v_cvt_pk_bf16_f32 v3, v4, v5
	global_store_dwordx2 v[12:13], v[2:3], off offset:256 nt
	s_waitcnt vmcnt(15) lgkmcnt(0)
	v_pk_add_f32 v[2:3], v[68:69], v[8:9]
	v_pk_add_f32 v[4:5], v[66:67], v[6:7]
	s_nop 0
	v_cvt_pk_bf16_f32 v4, v4, v5
	v_cvt_pk_bf16_f32 v5, v2, v3
	global_store_dwordx2 v[10:11], v[4:5], off offset:256 nt
	s_cbranch_scc1 .LBB0_831
	s_andn2_b64 vcc, exec, s[48:49]
	s_cbranch_vccnz .LBB0_830
	s_barrier
	s_branch .LBB0_830
